# v4 plus prologue: 32 per-item gain loads issued as one batch with a single wait; accumulator zeroing with 64-bit moves
# speedup vs baseline: 1.0055x; 1.0012x over previous
; template <class Epi, class Sched, bool ALIGN_EPI = false, bool SP2 = false>
; __device__ __forceinline__ void gemm_phase(PG8_LAS unsigned char* lds, const Gemm g, const Sched& S, const Epi& E, const int wave_in) {
;     ...
;     f32x4 acc[2][2][4][2];
; #pragma unroll
;     for (int a = 0; a < 2; ++a)
; #pragma unroll
;         for (int b = 0; b < 2; ++b)
; #pragma unroll
;             for (int m = 0; m < 4; ++m)
; #pragma unroll
;                 for (int n = 0; n < 2; ++n) acc[a][b][m][n] = (f32x4){0.f, 0.f, 0.f, 0.f};
;     ...
;         const bool has_next = S.next(ui + 1, nxt);
;         const char* nA = has_next ? (const char*)g.A + (size_t)nxt.pm * tstep : cA; const char* nB = has_next ? (const char*)g.Bt + (size_t)nxt.pn * tstep : cB;
;         for (int t = 0; t < nt; t += 2) {
;             const bool last = (t == nt - 2);
;             const char* a1 = cA + (size_t)(t + 1) * kstep;
;             const char* a2 = last ? nA : cA + (size_t)(t + 2) * kstep; const char* b2 = last ? nB : cB + (size_t)(t + 2) * kstep;
.LBB0_30:
	s_ashr_i32 s37, s36, 31
	s_lshl_b64 s[10:11], s[36:37], 20
	v_readlane_b32 s28, v251, 28
	v_readlane_b32 s29, v251, 29
	s_add_u32 s48, s28, s10
	s_addc_u32 s49, s29, s11
	s_and_b64 s[10:11], s[38:39], exec
	s_cselect_b32 s37, s49, s5
	s_cselect_b32 s68, s48, s4
	s_ashr_i32 s31, s30, 31
	s_lshl_b64 s[10:11], s[30:31], 20
	s_add_u32 s28, s12, s10
	s_addc_u32 s29, s13, s11
	s_and_b64 s[10:11], s[38:39], exec
	s_cselect_b32 s31, s29, s3
	s_cselect_b32 s69, s28, s2
	s_add_u32 s70, s2, 0x100
	s_addc_u32 s71, s3, 0
	s_add_u32 s2, s4, 0x80080
	s_addc_u32 s3, s5, 0
	s_mov_b32 s72, -2
	v_mov_b64_e32 v[0:1], 0
	v_mov_b64_e32 v[2:3], 0
	v_mov_b64_e32 v[4:5], 0
	v_mov_b64_e32 v[6:7], 0
	v_mov_b64_e32 v[8:9], 0
	v_mov_b64_e32 v[10:11], 0
	v_mov_b64_e32 v[12:13], 0
	v_mov_b64_e32 v[14:15], 0
	v_mov_b64_e32 v[16:17], 0
	v_mov_b64_e32 v[18:19], 0
	v_mov_b64_e32 v[20:21], 0
	v_mov_b64_e32 v[22:23], 0
	v_mov_b64_e32 v[24:25], 0
	v_mov_b64_e32 v[26:27], 0
	v_mov_b64_e32 v[28:29], 0
	v_mov_b64_e32 v[30:31], 0
	v_mov_b64_e32 v[32:33], 0
	v_mov_b64_e32 v[34:35], 0
	v_mov_b64_e32 v[36:37], 0
	v_mov_b64_e32 v[38:39], 0
	v_mov_b64_e32 v[40:41], 0
	v_mov_b64_e32 v[42:43], 0
	v_mov_b64_e32 v[44:45], 0
	v_mov_b64_e32 v[46:47], 0
	v_mov_b64_e32 v[48:49], 0
	v_mov_b64_e32 v[50:51], 0
	v_mov_b64_e32 v[52:53], 0
	v_mov_b64_e32 v[54:55], 0
	v_mov_b64_e32 v[56:57], 0
	v_mov_b64_e32 v[58:59], 0
	v_mov_b64_e32 v[60:61], 0
	v_mov_b64_e32 v[62:63], 0
	v_mov_b64_e32 v[64:65], 0
	v_mov_b64_e32 v[66:67], 0
	v_mov_b64_e32 v[68:69], 0
	v_mov_b64_e32 v[70:71], 0
	v_mov_b64_e32 v[72:73], 0
	v_mov_b64_e32 v[74:75], 0
	v_mov_b64_e32 v[76:77], 0
	v_mov_b64_e32 v[78:79], 0
	v_mov_b64_e32 v[80:81], 0
	v_mov_b64_e32 v[82:83], 0
	v_mov_b64_e32 v[84:85], 0
	v_mov_b64_e32 v[86:87], 0
	v_mov_b64_e32 v[88:89], 0
	v_mov_b64_e32 v[90:91], 0
	v_mov_b64_e32 v[92:93], 0
	v_mov_b64_e32 v[94:95], 0
	v_mov_b64_e32 v[96:97], 0
	v_mov_b64_e32 v[98:99], 0
	v_mov_b64_e32 v[100:101], 0
	v_mov_b64_e32 v[102:103], 0
	v_mov_b64_e32 v[104:105], 0
	v_mov_b64_e32 v[106:107], 0
	v_mov_b64_e32 v[108:109], 0
	v_mov_b64_e32 v[110:111], 0
	v_mov_b64_e32 v[112:113], 0
	v_mov_b64_e32 v[114:115], 0
	v_mov_b64_e32 v[116:117], 0
	v_mov_b64_e32 v[118:119], 0
	v_mov_b64_e32 v[120:121], 0
	v_mov_b64_e32 v[122:123], 0
	v_mov_b64_e32 v[124:125], 0
	v_mov_b64_e32 v[126:127], 0

; template <class Epi, class Sched, bool ALIGN_EPI = false, bool SP2 = false>
; __device__ __forceinline__ void gemm_phase(PG8_LAS unsigned char* lds, const Gemm g, const Sched& S, const Epi& E, const int wave_in) {
;     ...
; #pragma unroll
;         for (int a = 0; a < 2; ++a)
; #pragma unroll
;             for (int b = 0; b < 2; ++b)
; #pragma unroll
;                 for (int m = 0; m < 4; ++m)
; #pragma unroll
;                     for (int n = 0; n < 2; ++n) acc[a][b][m][n] = (f32x4){0.f, 0.f, 0.f, 0.f};
;         cur = nxt; cA = nA; cB = nB; ++ui;
.LBB0_58:
	s_add_u32 s44, s20, 0x100
	s_addc_u32 s45, s21, 0
	s_add_u32 s20, s24, 0x80
	s_addc_u32 s21, s25, 0
	s_mov_b32 s24, 0
	s_waitcnt lgkmcnt(0)
	v_mov_b64_e32 v[0:1], 0
	v_mov_b64_e32 v[2:3], 0
	v_mov_b64_e32 v[4:5], 0
	v_mov_b64_e32 v[6:7], 0
	v_mov_b64_e32 v[8:9], 0
	v_mov_b64_e32 v[10:11], 0
	v_mov_b64_e32 v[12:13], 0
	v_mov_b64_e32 v[14:15], 0
	v_mov_b64_e32 v[16:17], 0
	v_mov_b64_e32 v[18:19], 0
	v_mov_b64_e32 v[20:21], 0
	v_mov_b64_e32 v[22:23], 0
	v_mov_b64_e32 v[24:25], 0
	v_mov_b64_e32 v[26:27], 0
	v_mov_b64_e32 v[28:29], 0
	v_mov_b64_e32 v[30:31], 0
	v_mov_b64_e32 v[32:33], 0
	v_mov_b64_e32 v[34:35], 0
	v_mov_b64_e32 v[36:37], 0
	v_mov_b64_e32 v[38:39], 0
	v_mov_b64_e32 v[40:41], 0
	v_mov_b64_e32 v[42:43], 0
	v_mov_b64_e32 v[44:45], 0
	v_mov_b64_e32 v[46:47], 0
	v_mov_b64_e32 v[48:49], 0
	v_mov_b64_e32 v[50:51], 0
	v_mov_b64_e32 v[52:53], 0
	v_mov_b64_e32 v[54:55], 0
	v_mov_b64_e32 v[56:57], 0
	v_mov_b64_e32 v[58:59], 0
	v_mov_b64_e32 v[60:61], 0
	v_mov_b64_e32 v[62:63], 0
	v_mov_b64_e32 v[64:65], 0
	v_mov_b64_e32 v[66:67], 0
	v_mov_b64_e32 v[68:69], 0
	v_mov_b64_e32 v[70:71], 0
	v_mov_b64_e32 v[72:73], 0
	v_mov_b64_e32 v[74:75], 0
	v_mov_b64_e32 v[76:77], 0
	v_mov_b64_e32 v[78:79], 0
	v_mov_b64_e32 v[80:81], 0
	v_mov_b64_e32 v[82:83], 0
	v_mov_b64_e32 v[84:85], 0
	v_mov_b64_e32 v[86:87], 0
	v_mov_b64_e32 v[88:89], 0
	v_mov_b64_e32 v[90:91], 0
	v_mov_b64_e32 v[92:93], 0
	v_mov_b64_e32 v[94:95], 0
	v_mov_b64_e32 v[96:97], 0
	v_mov_b64_e32 v[98:99], 0
	v_mov_b64_e32 v[100:101], 0
	v_mov_b64_e32 v[102:103], 0
	v_mov_b64_e32 v[104:105], 0
	v_mov_b64_e32 v[106:107], 0
	v_mov_b64_e32 v[108:109], 0
	v_mov_b64_e32 v[110:111], 0
	v_mov_b64_e32 v[112:113], 0
	v_mov_b64_e32 v[114:115], 0
	v_mov_b64_e32 v[116:117], 0
	v_mov_b64_e32 v[118:119], 0
	v_mov_b64_e32 v[124:125], 0
	v_mov_b64_e32 v[126:127], 0
	v_mov_b64_e32 v[128:129], 0
	v_mov_b64_e32 v[130:131], 0

; template <class Epi, class Sched, bool ALIGN_EPI = false, bool SP2 = false>
; __device__ __forceinline__ void gemm_phase(PG8_LAS unsigned char* lds, const Gemm g, const Sched& S, const Epi& E, const int wave_in) {
;     ...
;         const char* nA = has_next ? (const char*)g.A + (size_t)nxt.pm * tstep : cA; const char* nB = has_next ? (const char*)g.Bt + (size_t)nxt.pn * tstep : cB;
;         for (int t = 0; t < nt; t += 2) {
;             const bool last = (t == nt - 2);
;             const char* a1 = cA + (size_t)(t + 1) * kstep;
;             const char* a2 = last ? nA : cA + (size_t)(t + 2) * kstep; const char* b2 = last ? nB : cB + (size_t)(t + 2) * kstep;
;             const char* a3 = a2 + kstep; const char* b3 = b2 + kstep;
;     ...
;         for (int a = 0; a < 2; ++a)
; #pragma unroll
;             for (int b = 0; b < 2; ++b)
; #pragma unroll
;                 for (int m = 0; m < 4; ++m)
; #pragma unroll
;                     for (int n = 0; n < 2; ++n) acc[a][b][m][n] = (f32x4){0.f, 0.f, 0.f, 0.f};
.LBB0_352:
	s_ashr_i32 s3, s2, 31
	s_lshl_b64 s[10:11], s[2:3], 20
	s_add_u32 s10, s6, s10
	s_addc_u32 s11, s7, s11
	s_and_b64 s[16:17], s[40:41], exec
	s_cselect_b32 s3, s11, s47
	s_cselect_b32 s8, s10, s46
	s_ashr_i32 s27, s26, 31
	s_lshl_b64 s[16:17], s[26:27], 20
	s_add_u32 s30, s92, s16
	s_addc_u32 s31, s93, s17
	s_and_b64 s[16:17], s[40:41], exec
	s_cselect_b32 s27, s31, s45
	s_cselect_b32 s43, s30, s44
	s_add_u32 s79, s44, 0x100
	s_addc_u32 s80, s45, 0
	s_add_u32 s44, s46, 0x80080
	s_addc_u32 s45, s47, 0
	s_mov_b32 s81, -2
	v_mov_b64_e32 v[0:1], 0
	v_mov_b64_e32 v[2:3], 0
	v_mov_b64_e32 v[4:5], 0
	v_mov_b64_e32 v[6:7], 0
	v_mov_b64_e32 v[8:9], 0
	v_mov_b64_e32 v[10:11], 0
	v_mov_b64_e32 v[12:13], 0
	v_mov_b64_e32 v[14:15], 0
	v_mov_b64_e32 v[16:17], 0
	v_mov_b64_e32 v[18:19], 0
	v_mov_b64_e32 v[20:21], 0
	v_mov_b64_e32 v[22:23], 0
	v_mov_b64_e32 v[24:25], 0
	v_mov_b64_e32 v[26:27], 0
	v_mov_b64_e32 v[28:29], 0
	v_mov_b64_e32 v[30:31], 0
	v_mov_b64_e32 v[32:33], 0
	v_mov_b64_e32 v[34:35], 0
	v_mov_b64_e32 v[36:37], 0
	v_mov_b64_e32 v[38:39], 0
	v_mov_b64_e32 v[40:41], 0
	v_mov_b64_e32 v[42:43], 0
	v_mov_b64_e32 v[44:45], 0
	v_mov_b64_e32 v[46:47], 0
	v_mov_b64_e32 v[48:49], 0
	v_mov_b64_e32 v[50:51], 0
	v_mov_b64_e32 v[52:53], 0
	v_mov_b64_e32 v[54:55], 0
	v_mov_b64_e32 v[56:57], 0
	v_mov_b64_e32 v[58:59], 0
	v_mov_b64_e32 v[60:61], 0
	v_mov_b64_e32 v[62:63], 0
	v_mov_b64_e32 v[64:65], 0
	v_mov_b64_e32 v[66:67], 0
	v_mov_b64_e32 v[68:69], 0
	v_mov_b64_e32 v[70:71], 0
	v_mov_b64_e32 v[72:73], 0
	v_mov_b64_e32 v[74:75], 0
	v_mov_b64_e32 v[76:77], 0
	v_mov_b64_e32 v[78:79], 0
	v_mov_b64_e32 v[80:81], 0
	v_mov_b64_e32 v[82:83], 0
	v_mov_b64_e32 v[84:85], 0
	v_mov_b64_e32 v[86:87], 0
	v_mov_b64_e32 v[88:89], 0
	v_mov_b64_e32 v[90:91], 0
	v_mov_b64_e32 v[92:93], 0
	v_mov_b64_e32 v[94:95], 0
	v_mov_b64_e32 v[96:97], 0
	v_mov_b64_e32 v[98:99], 0
	v_mov_b64_e32 v[100:101], 0
	v_mov_b64_e32 v[102:103], 0
	v_mov_b64_e32 v[104:105], 0
	v_mov_b64_e32 v[106:107], 0
	v_mov_b64_e32 v[108:109], 0
	v_mov_b64_e32 v[110:111], 0
	v_mov_b64_e32 v[112:113], 0
	v_mov_b64_e32 v[114:115], 0
	v_mov_b64_e32 v[116:117], 0
	v_mov_b64_e32 v[118:119], 0
	v_mov_b64_e32 v[120:121], 0
	v_mov_b64_e32 v[122:123], 0
	v_mov_b64_e32 v[124:125], 0
	v_mov_b64_e32 v[126:127], 0

; template <class Epi, class Sched, bool ALIGN_EPI = false, bool SP2 = false>
; __device__ __forceinline__ void gemm_phase(PG8_LAS unsigned char* lds, const Gemm g, const Sched& S, const Epi& E, const int wave_in) {
;     ...
;         const char* nA = has_next ? (const char*)g.A + (size_t)nxt.pm * tstep : cA; const char* nB = has_next ? (const char*)g.Bt + (size_t)nxt.pn * tstep : cB;
;         for (int t = 0; t < nt; t += 2) {
;             const bool last = (t == nt - 2);
;             const char* a1 = cA + (size_t)(t + 1) * kstep;
;             const char* a2 = last ? nA : cA + (size_t)(t + 2) * kstep; const char* b2 = last ? nB : cB + (size_t)(t + 2) * kstep;
;             const char* a3 = a2 + kstep; const char* b3 = b2 + kstep;
;     ...
;         for (int a = 0; a < 2; ++a)
; #pragma unroll
;             for (int b = 0; b < 2; ++b)
; #pragma unroll
;                 for (int m = 0; m < 4; ++m)
; #pragma unroll
;                     for (int n = 0; n < 2; ++n) acc[a][b][m][n] = (f32x4){0.f, 0.f, 0.f, 0.f};
.LBB0_529:
	s_ashr_i32 s25, s24, 31
	s_lshl_b64 s[26:27], s[24:25], 20
	s_add_u32 s26, s4, s26
	s_addc_u32 s27, s5, s27
	s_and_b64 s[28:29], s[38:39], exec
	s_cselect_b32 s25, s27, s41
	s_cselect_b32 s83, s26, s40
	s_ashr_i32 s23, s22, 31
	s_lshl_b64 s[28:29], s[22:23], 20
	s_add_u32 s28, s10, s28
	s_addc_u32 s29, s11, s29
	s_and_b64 s[42:43], s[38:39], exec
	s_cselect_b32 s23, s29, s37
	s_cselect_b32 s87, s28, s36
	s_add_u32 s88, s36, 0x100
	s_addc_u32 s92, s37, 0
	s_add_u32 s36, s40, 0x80080
	s_addc_u32 s37, s41, 0
	s_mov_b32 s93, -2
	v_mov_b64_e32 v[0:1], 0
	v_mov_b64_e32 v[2:3], 0
	v_mov_b64_e32 v[4:5], 0
	v_mov_b64_e32 v[6:7], 0
	v_mov_b64_e32 v[8:9], 0
	v_mov_b64_e32 v[10:11], 0
	v_mov_b64_e32 v[12:13], 0
	v_mov_b64_e32 v[14:15], 0
	v_mov_b64_e32 v[16:17], 0
	v_mov_b64_e32 v[18:19], 0
	v_mov_b64_e32 v[20:21], 0
	v_mov_b64_e32 v[22:23], 0
	v_mov_b64_e32 v[24:25], 0
	v_mov_b64_e32 v[26:27], 0
	v_mov_b64_e32 v[28:29], 0
	v_mov_b64_e32 v[30:31], 0
	v_mov_b64_e32 v[32:33], 0
	v_mov_b64_e32 v[34:35], 0
	v_mov_b64_e32 v[36:37], 0
	v_mov_b64_e32 v[38:39], 0
	v_mov_b64_e32 v[40:41], 0
	v_mov_b64_e32 v[42:43], 0
	v_mov_b64_e32 v[44:45], 0
	v_mov_b64_e32 v[46:47], 0
	v_mov_b64_e32 v[48:49], 0
	v_mov_b64_e32 v[50:51], 0
	v_mov_b64_e32 v[52:53], 0
	v_mov_b64_e32 v[54:55], 0
	v_mov_b64_e32 v[56:57], 0
	v_mov_b64_e32 v[58:59], 0
	v_mov_b64_e32 v[60:61], 0
	v_mov_b64_e32 v[62:63], 0
	v_mov_b64_e32 v[64:65], 0
	v_mov_b64_e32 v[66:67], 0
	v_mov_b64_e32 v[68:69], 0
	v_mov_b64_e32 v[70:71], 0
	v_mov_b64_e32 v[72:73], 0
	v_mov_b64_e32 v[74:75], 0
	v_mov_b64_e32 v[76:77], 0
	v_mov_b64_e32 v[78:79], 0
	v_mov_b64_e32 v[80:81], 0
	v_mov_b64_e32 v[82:83], 0
	v_mov_b64_e32 v[84:85], 0
	v_mov_b64_e32 v[86:87], 0
	v_mov_b64_e32 v[88:89], 0
	v_mov_b64_e32 v[90:91], 0
	v_mov_b64_e32 v[92:93], 0
	v_mov_b64_e32 v[94:95], 0
	v_mov_b64_e32 v[96:97], 0
	v_mov_b64_e32 v[98:99], 0
	v_mov_b64_e32 v[100:101], 0
	v_mov_b64_e32 v[102:103], 0
	v_mov_b64_e32 v[104:105], 0
	v_mov_b64_e32 v[106:107], 0
	v_mov_b64_e32 v[108:109], 0
	v_mov_b64_e32 v[110:111], 0
	v_mov_b64_e32 v[112:113], 0
	v_mov_b64_e32 v[114:115], 0
	v_mov_b64_e32 v[116:117], 0
	v_mov_b64_e32 v[118:119], 0
	v_mov_b64_e32 v[120:121], 0
	v_mov_b64_e32 v[122:123], 0
	v_mov_b64_e32 v[124:125], 0
	v_mov_b64_e32 v[126:127], 0

; __device__ __forceinline__ void tr_store(const TrItem& d, const float (&v)[32], LAS float* scr, int lane) {
;     ...
;     for (int i = 0; i < 32; ++i) { const int kk = 2 * i + (lane >> 5); const float gk = d.gain ? d.gain[d.k0 + kk] : 1.f; scr[kk * 33 + (lane & 31)] = v[i] * gk; }
.LBB0_577:
	v_add_u32_e32 v84, s4, v0
	v_ashrrev_i32_e32 v85, 31, v84
	v_lshl_add_u64 v[84:85], v[84:85], 2, s[6:7]
	global_load_dword v100, v[84:85], off
	global_load_dword v101, v[84:85], off offset:8
	global_load_dword v102, v[84:85], off offset:16
	global_load_dword v103, v[84:85], off offset:24
	global_load_dword v104, v[84:85], off offset:32
	global_load_dword v105, v[84:85], off offset:40
	global_load_dword v106, v[84:85], off offset:48
	global_load_dword v107, v[84:85], off offset:56
	global_load_dword v108, v[84:85], off offset:64
	global_load_dword v109, v[84:85], off offset:72
	global_load_dword v110, v[84:85], off offset:80
	global_load_dword v111, v[84:85], off offset:88
	global_load_dword v112, v[84:85], off offset:96
	global_load_dword v113, v[84:85], off offset:104
	global_load_dword v114, v[84:85], off offset:112
	global_load_dword v115, v[84:85], off offset:120
	global_load_dword v116, v[84:85], off offset:128
	global_load_dword v117, v[84:85], off offset:136
	global_load_dword v118, v[84:85], off offset:144
	global_load_dword v119, v[84:85], off offset:152
	global_load_dword v120, v[84:85], off offset:160
	global_load_dword v121, v[84:85], off offset:168
	global_load_dword v122, v[84:85], off offset:176
	global_load_dword v123, v[84:85], off offset:184
	global_load_dword v124, v[84:85], off offset:192
	global_load_dword v125, v[84:85], off offset:200
	global_load_dword v126, v[84:85], off offset:208
	global_load_dword v127, v[84:85], off offset:216
	global_load_dword v128, v[84:85], off offset:224
	global_load_dword v129, v[84:85], off offset:232
	global_load_dword v130, v[84:85], off offset:240
	global_load_dword v131, v[84:85], off offset:248
	s_waitcnt vmcnt(0)
	v_mov_b32_e32 v86, v100
	v_mov_b32_e32 v83, v101
	v_mul_f32_e32 v84, v82, v86
	ds_write_b32 v13, v84
	s_cbranch_execnz .LBB0_579

; __device__ __forceinline__ void tr_store(const TrItem& d, const float (&v)[32], LAS float* scr, int lane) {
;     ...
;     for (int i = 0; i < 32; ++i) { const int kk = 2 * i + (lane >> 5); const float gk = d.gain ? d.gain[d.k0 + kk] : 1.f; scr[kk * 33 + (lane & 31)] = v[i] * gk; }
.LBB0_579:
	s_waitcnt vmcnt(0)
	v_cndmask_b32_e64 v82, 0, 1, s[18:19]
	s_waitcnt vmcnt(0)
	v_mul_f32_e32 v81, v81, v83
	v_cmp_ne_u32_e64 s[38:39], 1, v82
	s_andn2_b64 vcc, exec, s[18:19]
	ds_write_b32 v9, v81
	s_cbranch_vccnz .LBB0_638
	s_ashr_i32 s5, s4, 31
	v_lshl_add_u64 v[82:83], s[4:5], 0, v[0:1]
	v_lshl_add_u64 v[82:83], v[82:83], 2, s[6:7]
	v_mov_b32_e32 v84, v102
	v_mov_b32_e32 v81, v103
	v_mul_f32_e32 v82, v79, v84
	ds_write_b32 v14, v82
	s_cbranch_execnz .LBB0_582

; __device__ __forceinline__ void tr_store(const TrItem& d, const float (&v)[32], LAS float* scr, int lane) {
;     ...
;     for (int i = 0; i < 32; ++i) { const int kk = 2 * i + (lane >> 5); const float gk = d.gain ? d.gain[d.k0 + kk] : 1.f; scr[kk * 33 + (lane & 31)] = v[i] * gk; }
.LBB0_582:
	s_waitcnt vmcnt(0)
	v_mul_f32_e32 v79, v80, v81
	s_and_b64 vcc, exec, s[38:39]
	ds_write_b32 v10, v79
	s_cbranch_vccnz .LBB0_639
	s_ashr_i32 s5, s4, 31
	v_lshl_add_u64 v[80:81], s[4:5], 0, v[0:1]
	v_lshl_add_u64 v[80:81], v[80:81], 2, s[6:7]
	v_mov_b32_e32 v82, v104
	v_mov_b32_e32 v79, v105
	v_mul_f32_e32 v80, v78, v82
	ds_write_b32 v15, v80
	s_cbranch_execnz .LBB0_585

; __device__ __forceinline__ void tr_store(const TrItem& d, const float (&v)[32], LAS float* scr, int lane) {
;     ...
;     for (int i = 0; i < 32; ++i) { const int kk = 2 * i + (lane >> 5); const float gk = d.gain ? d.gain[d.k0 + kk] : 1.f; scr[kk * 33 + (lane & 31)] = v[i] * gk; }
.LBB0_585:
	s_waitcnt vmcnt(0)
	v_mul_f32_e32 v77, v77, v79
	s_and_b64 vcc, exec, s[38:39]
	ds_write_b32 v11, v77
	s_cbranch_vccnz .LBB0_640
	s_ashr_i32 s5, s4, 31
	v_lshl_add_u64 v[78:79], s[4:5], 0, v[0:1]
	v_lshl_add_u64 v[78:79], v[78:79], 2, s[6:7]
	v_mov_b32_e32 v80, v106
	v_mov_b32_e32 v77, v107
	v_mul_f32_e32 v78, v76, v80
	ds_write_b32 v16, v78
	s_cbranch_execnz .LBB0_588

; __device__ __forceinline__ void tr_store(const TrItem& d, const float (&v)[32], LAS float* scr, int lane) {
;     ...
;     for (int i = 0; i < 32; ++i) { const int kk = 2 * i + (lane >> 5); const float gk = d.gain ? d.gain[d.k0 + kk] : 1.f; scr[kk * 33 + (lane & 31)] = v[i] * gk; }
.LBB0_588:
	s_waitcnt vmcnt(0)
	v_mul_f32_e32 v75, v75, v77
	s_and_b64 vcc, exec, s[38:39]
	ds_write_b32 v12, v75
	s_cbranch_vccnz .LBB0_641
	s_ashr_i32 s5, s4, 31
	v_lshl_add_u64 v[76:77], s[4:5], 0, v[0:1]
	v_lshl_add_u64 v[76:77], v[76:77], 2, s[6:7]
	v_mov_b32_e32 v78, v108
	v_mov_b32_e32 v75, v109
	v_mul_f32_e32 v76, v74, v78
	ds_write_b32 v17, v76
	s_cbranch_execnz .LBB0_591

; __device__ __forceinline__ void tr_store(const TrItem& d, const float (&v)[32], LAS float* scr, int lane) {
;     ...
;     for (int i = 0; i < 32; ++i) { const int kk = 2 * i + (lane >> 5); const float gk = d.gain ? d.gain[d.k0 + kk] : 1.f; scr[kk * 33 + (lane & 31)] = v[i] * gk; }
.LBB0_591:
	s_waitcnt vmcnt(0)
	v_mul_f32_e32 v73, v73, v75
	s_and_b64 vcc, exec, s[38:39]
	ds_write_b32 v17, v73 offset:264
	s_cbranch_vccnz .LBB0_642
	s_ashr_i32 s5, s4, 31
	v_lshl_add_u64 v[74:75], s[4:5], 0, v[0:1]
	v_lshl_add_u64 v[74:75], v[74:75], 2, s[6:7]
	v_mov_b32_e32 v76, v110
	v_mov_b32_e32 v73, v111
	v_mul_f32_e32 v74, v72, v76
	ds_write_b32 v17, v74 offset:528
	s_cbranch_execnz .LBB0_594

; __device__ __forceinline__ void tr_store(const TrItem& d, const float (&v)[32], LAS float* scr, int lane) {
;     ...
;     for (int i = 0; i < 32; ++i) { const int kk = 2 * i + (lane >> 5); const float gk = d.gain ? d.gain[d.k0 + kk] : 1.f; scr[kk * 33 + (lane & 31)] = v[i] * gk; }
.LBB0_594:
	s_waitcnt vmcnt(0)
	v_mul_f32_e32 v71, v71, v73
	s_and_b64 vcc, exec, s[38:39]
	ds_write_b32 v17, v71 offset:792
	s_cbranch_vccnz .LBB0_643
	s_ashr_i32 s5, s4, 31
	v_lshl_add_u64 v[72:73], s[4:5], 0, v[0:1]
	v_lshl_add_u64 v[72:73], v[72:73], 2, s[6:7]
	v_mov_b32_e32 v74, v112
	v_mov_b32_e32 v71, v113
	v_mul_f32_e32 v72, v70, v74
	ds_write_b32 v17, v72 offset:1056
	s_cbranch_execnz .LBB0_597

; __device__ __forceinline__ void tr_store(const TrItem& d, const float (&v)[32], LAS float* scr, int lane) {
;     ...
;     for (int i = 0; i < 32; ++i) { const int kk = 2 * i + (lane >> 5); const float gk = d.gain ? d.gain[d.k0 + kk] : 1.f; scr[kk * 33 + (lane & 31)] = v[i] * gk; }
.LBB0_597:
	s_waitcnt vmcnt(0)
	v_mul_f32_e32 v69, v69, v71
	s_and_b64 vcc, exec, s[38:39]
	ds_write_b32 v17, v69 offset:1320
	s_cbranch_vccnz .LBB0_644
	s_ashr_i32 s5, s4, 31
	v_lshl_add_u64 v[70:71], s[4:5], 0, v[0:1]
	v_lshl_add_u64 v[70:71], v[70:71], 2, s[6:7]
	v_mov_b32_e32 v72, v114
	v_mov_b32_e32 v69, v115
	v_mul_f32_e32 v70, v68, v72
	ds_write_b32 v17, v70 offset:1584
	s_cbranch_execnz .LBB0_600

; __device__ __forceinline__ void tr_store(const TrItem& d, const float (&v)[32], LAS float* scr, int lane) {
;     ...
;     for (int i = 0; i < 32; ++i) { const int kk = 2 * i + (lane >> 5); const float gk = d.gain ? d.gain[d.k0 + kk] : 1.f; scr[kk * 33 + (lane & 31)] = v[i] * gk; }
.LBB0_600:
	s_waitcnt vmcnt(0)
	v_mul_f32_e32 v67, v67, v69
	s_and_b64 vcc, exec, s[38:39]
	ds_write_b32 v17, v67 offset:1848
	s_cbranch_vccnz .LBB0_645
	s_ashr_i32 s5, s4, 31
	v_lshl_add_u64 v[68:69], s[4:5], 0, v[0:1]
	v_lshl_add_u64 v[68:69], v[68:69], 2, s[6:7]
	v_mov_b32_e32 v70, v116
	v_mov_b32_e32 v67, v117
	v_mul_f32_e32 v68, v66, v70
	ds_write_b32 v17, v68 offset:2112
	s_cbranch_execnz .LBB0_603

; __device__ __forceinline__ void tr_store(const TrItem& d, const float (&v)[32], LAS float* scr, int lane) {
;     ...
;     for (int i = 0; i < 32; ++i) { const int kk = 2 * i + (lane >> 5); const float gk = d.gain ? d.gain[d.k0 + kk] : 1.f; scr[kk * 33 + (lane & 31)] = v[i] * gk; }
.LBB0_603:
	s_waitcnt vmcnt(0)
	v_mul_f32_e32 v65, v65, v67
	s_and_b64 vcc, exec, s[38:39]
	ds_write_b32 v17, v65 offset:2376
	s_cbranch_vccnz .LBB0_646
	s_ashr_i32 s5, s4, 31
	v_lshl_add_u64 v[66:67], s[4:5], 0, v[0:1]
	v_lshl_add_u64 v[66:67], v[66:67], 2, s[6:7]
	v_mov_b32_e32 v68, v118
	v_mov_b32_e32 v65, v119
	v_mul_f32_e32 v66, v64, v68
	ds_write_b32 v17, v66 offset:2640
	s_cbranch_execnz .LBB0_606

; __device__ __forceinline__ void tr_store(const TrItem& d, const float (&v)[32], LAS float* scr, int lane) {
;     ...
;     for (int i = 0; i < 32; ++i) { const int kk = 2 * i + (lane >> 5); const float gk = d.gain ? d.gain[d.k0 + kk] : 1.f; scr[kk * 33 + (lane & 31)] = v[i] * gk; }
.LBB0_606:
	s_waitcnt vmcnt(0)
	v_mul_f32_e32 v63, v63, v65
	s_and_b64 vcc, exec, s[38:39]
	ds_write_b32 v17, v63 offset:2904
	s_cbranch_vccnz .LBB0_647
	s_ashr_i32 s5, s4, 31
	v_lshl_add_u64 v[64:65], s[4:5], 0, v[0:1]
	v_lshl_add_u64 v[64:65], v[64:65], 2, s[6:7]
	v_mov_b32_e32 v66, v120
	v_mov_b32_e32 v63, v121
	v_mul_f32_e32 v64, v62, v66
	ds_write_b32 v17, v64 offset:3168
	s_cbranch_execnz .LBB0_609

; __device__ __forceinline__ void tr_store(const TrItem& d, const float (&v)[32], LAS float* scr, int lane) {
;     ...
;     for (int i = 0; i < 32; ++i) { const int kk = 2 * i + (lane >> 5); const float gk = d.gain ? d.gain[d.k0 + kk] : 1.f; scr[kk * 33 + (lane & 31)] = v[i] * gk; }
.LBB0_609:
	s_waitcnt vmcnt(0)
	v_mul_f32_e32 v61, v61, v63
	s_and_b64 vcc, exec, s[38:39]
	ds_write_b32 v17, v61 offset:3432
	s_cbranch_vccnz .LBB0_648
	s_ashr_i32 s5, s4, 31
	v_lshl_add_u64 v[62:63], s[4:5], 0, v[0:1]
	v_lshl_add_u64 v[62:63], v[62:63], 2, s[6:7]
	v_mov_b32_e32 v64, v122
	v_mov_b32_e32 v61, v123
	v_mul_f32_e32 v62, v60, v64
	ds_write_b32 v17, v62 offset:3696
	s_cbranch_execnz .LBB0_612

; __device__ __forceinline__ void tr_store(const TrItem& d, const float (&v)[32], LAS float* scr, int lane) {
;     ...
;     for (int i = 0; i < 32; ++i) { const int kk = 2 * i + (lane >> 5); const float gk = d.gain ? d.gain[d.k0 + kk] : 1.f; scr[kk * 33 + (lane & 31)] = v[i] * gk; }
.LBB0_612:
	s_waitcnt vmcnt(0)
	v_mul_f32_e32 v59, v59, v61
	s_and_b64 vcc, exec, s[38:39]
	ds_write_b32 v17, v59 offset:3960
	s_cbranch_vccnz .LBB0_649
	s_ashr_i32 s5, s4, 31
	v_lshl_add_u64 v[60:61], s[4:5], 0, v[0:1]
	v_lshl_add_u64 v[60:61], v[60:61], 2, s[6:7]
	v_mov_b32_e32 v62, v124
	v_mov_b32_e32 v59, v125
	v_mul_f32_e32 v60, v58, v62
	ds_write_b32 v17, v60 offset:4224
	s_cbranch_execnz .LBB0_615

; __device__ __forceinline__ void tr_store(const TrItem& d, const float (&v)[32], LAS float* scr, int lane) {
;     ...
;     for (int i = 0; i < 32; ++i) { const int kk = 2 * i + (lane >> 5); const float gk = d.gain ? d.gain[d.k0 + kk] : 1.f; scr[kk * 33 + (lane & 31)] = v[i] * gk; }
.LBB0_615:
	s_waitcnt vmcnt(0)
	v_mul_f32_e32 v57, v57, v59
	s_and_b64 vcc, exec, s[38:39]
	ds_write_b32 v17, v57 offset:4488
	s_cbranch_vccnz .LBB0_650
	s_ashr_i32 s5, s4, 31
	v_lshl_add_u64 v[58:59], s[4:5], 0, v[0:1]
	v_lshl_add_u64 v[58:59], v[58:59], 2, s[6:7]
	v_mov_b32_e32 v60, v126
	v_mov_b32_e32 v57, v127
	v_mul_f32_e32 v58, v56, v60
	ds_write_b32 v17, v58 offset:4752
	s_cbranch_execnz .LBB0_618

; __device__ __forceinline__ void tr_store(const TrItem& d, const float (&v)[32], LAS float* scr, int lane) {
;     ...
;     for (int i = 0; i < 32; ++i) { const int kk = 2 * i + (lane >> 5); const float gk = d.gain ? d.gain[d.k0 + kk] : 1.f; scr[kk * 33 + (lane & 31)] = v[i] * gk; }
.LBB0_618:
	s_waitcnt vmcnt(0)
	v_mul_f32_e32 v55, v55, v57
	s_and_b64 vcc, exec, s[38:39]
	ds_write_b32 v17, v55 offset:5016
	s_cbranch_vccnz .LBB0_651
	s_ashr_i32 s5, s4, 31
	v_lshl_add_u64 v[56:57], s[4:5], 0, v[0:1]
	v_lshl_add_u64 v[56:57], v[56:57], 2, s[6:7]
	v_mov_b32_e32 v58, v128
	v_mov_b32_e32 v55, v129
	v_mul_f32_e32 v56, v54, v58
	ds_write_b32 v17, v56 offset:5280
	s_cbranch_execnz .LBB0_621

; __device__ __forceinline__ void tr_store(const TrItem& d, const float (&v)[32], LAS float* scr, int lane) {
;     ...
;     for (int i = 0; i < 32; ++i) { const int kk = 2 * i + (lane >> 5); const float gk = d.gain ? d.gain[d.k0 + kk] : 1.f; scr[kk * 33 + (lane & 31)] = v[i] * gk; }
.LBB0_621:
	s_waitcnt vmcnt(0)
	v_mul_f32_e32 v53, v53, v55
	s_and_b64 vcc, exec, s[38:39]
	ds_write_b32 v17, v53 offset:5544
	s_cbranch_vccnz .LBB0_652
	s_ashr_i32 s5, s4, 31
	v_lshl_add_u64 v[54:55], s[4:5], 0, v[0:1]
	v_lshl_add_u64 v[54:55], v[54:55], 2, s[6:7]
	v_mov_b32_e32 v56, v130
	v_mov_b32_e32 v53, v131
	v_mul_f32_e32 v54, v52, v56
	ds_write_b32 v17, v54 offset:5808
	s_cbranch_execnz .LBB0_572
	s_branch .LBB0_653
